# lora: results transposed through the wave's free X-tile LDS region so adjacent lanes store contiguous bytes (DEC 64 B runs, AB+GG in one store)
# baseline (speedup 1.0000x reference)
; #define LAS __attribute__((address_space(3)))
; __device__ __forceinline__ unsigned pk2(float lo, float hi) { f32x2 v = {lo, hi}; bf16x2_t b = __builtin_convertvector(v, bf16x2_t); return __builtin_bit_cast(unsigned, b); }
; __device__ __forceinline__ float sigmoidf_(float x) { return frcp(1.f + fexp2(-1.4426950408889634f * x)); }
;     __device__ __forceinline__ const float* in(int i) const { return (const float*)ptr(i); }
; __device__ __forceinline__ void phase_lora(const Ctx& p, LAS unsigned char* lds) {
;     ...
;                 zshift8(p, ZRW, row, 1536 + c, m8, z);
; #pragma unroll
;                 for (int e = 0; e < 8; ++e) z[e] = cq == 0 ? tanhf(z[e]) : (cq == 1 ? z[e] : sigmoidf_(z[e]));
;                 u32x4 w; w.x = pk2(z[0], z[1]); w.y = pk2(z[2], z[3]); w.z = pk2(z[4], z[5]); w.w = pk2(z[6], z[7]);
;                 *(LAS u32x4*)(X + tt * 264 + c) = w;
;             }
;         }
;         asm volatile("s_waitcnt lgkmcnt(0)" ::: "memory");
;         bf16x8 bx[8];
; #pragma unroll
;         for (int ks = 0; ks < 8; ++ks) bx[ks] = *(const LAS bf16x8*)(X + q * 264 + ks * 32 + 8 * g);
;         const int row = r0 + q;
;         struct WF { bf16x8 w[2], a[2], gq[4]; f32x4 w0, a0; };
;         auto ldw = [&](WF& f, int nt) {
;             const int n = nt * 16 + q, c = nt * 16 + 4 * g;
; #pragma unroll
;             for (int ks = 0; ks < 2; ++ks) { f.w[ks] = *(const bf16x8*)(w2T + n * 64 + ks * 32 + 8 * g); f.a[ks] = *(const bf16x8*)(a2T + n * 64 + ks * 32 + 8 * g); }
; #pragma unroll
;             for (int ks = 0; ks < 4; ++ks) f.gq[ks] = *(const bf16x8*)(g2T + n * 128 + ks * 32 + 8 * g);
;             f.w0 = *(const f32x4*)(p.in(18) + c); f.a0 = *(const f32x4*)(p.in(20) + c);
;         };
;     ...
;             *(f32x4*)(DEC + (size_t)row * 512 + c) = dec;
;             *(u32x2*)(AB + (size_t)row * 512 + c) = (u32x2){pk2(av[0], av[1]), pk2(av[2], av[3])};
;             *(u32x2*)(GG + (size_t)row * 512 + c) = (u32x2){pk2(ag[0], ag[1]), pk2(ag[2], ag[3])};
.Llora_nf7:
	v_sub_f32_e32 v152, v152, v144
	v_sub_f32_e32 v153, v153, v145
	v_sub_f32_e32 v154, v154, v146
	v_sub_f32_e32 v155, v155, v147
	v_sub_f32_e32 v156, v156, v148
	v_sub_f32_e32 v157, v157, v149
	v_sub_f32_e32 v158, v158, v150
	v_sub_f32_e32 v159, v159, v151
	v_fmac_f32_e32 v144, v152, v136
	v_fmac_f32_e32 v145, v153, v137
	v_fmac_f32_e32 v146, v154, v138
	v_fmac_f32_e32 v147, v155, v139
	v_fmac_f32_e32 v148, v156, v140
	v_fmac_f32_e32 v149, v157, v141
	v_fmac_f32_e32 v150, v158, v142
	v_fmac_f32_e32 v151, v159, v143
	v_mul_f32_e32 v152, v7, v144
	v_mul_f32_e32 v153, v7, v145
	v_mul_f32_e32 v154, v7, v146
	v_mul_f32_e32 v155, v7, v147
	v_mul_f32_e32 v156, v7, v148
	v_mul_f32_e32 v157, v7, v149
	v_mul_f32_e32 v158, v7, v150
	v_mul_f32_e32 v159, v7, v151
	v_exp_f32_e32 v152, v152
	v_exp_f32_e32 v153, v153
	v_exp_f32_e32 v154, v154
	v_exp_f32_e32 v155, v155
	v_exp_f32_e32 v156, v156
	v_exp_f32_e32 v157, v157
	v_exp_f32_e32 v158, v158
	v_exp_f32_e32 v159, v159
	v_add_f32_e32 v152, 1.0, v152
	v_add_f32_e32 v153, 1.0, v153
	v_add_f32_e32 v154, 1.0, v154
	v_add_f32_e32 v155, 1.0, v155
	v_add_f32_e32 v156, 1.0, v156
	v_add_f32_e32 v157, 1.0, v157
	v_add_f32_e32 v158, 1.0, v158
	v_add_f32_e32 v159, 1.0, v159
	v_rcp_f32_e32 v152, v152
	v_rcp_f32_e32 v153, v153
	v_rcp_f32_e32 v154, v154
	v_rcp_f32_e32 v155, v155
	v_rcp_f32_e32 v156, v156
	v_rcp_f32_e32 v157, v157
	v_rcp_f32_e32 v158, v158
	v_rcp_f32_e32 v159, v159
	v_fma_f32 v152, v152, v8, v9
	v_fma_f32 v153, v153, v8, v9
	v_fma_f32 v154, v154, v8, v9
	v_fma_f32 v155, v155, v8, v9
	v_fma_f32 v156, v156, v8, v9
	v_fma_f32 v157, v157, v8, v9
	v_fma_f32 v158, v158, v8, v9
	v_fma_f32 v159, v159, v8, v9
	v_cndmask_b32_e64 v152, v152, v144, s[48:49]
	v_cndmask_b32_e64 v153, v153, v145, s[48:49]
	v_cndmask_b32_e64 v154, v154, v146, s[48:49]
	v_cndmask_b32_e64 v155, v155, v147, s[48:49]
	v_cndmask_b32_e64 v156, v156, v148, s[48:49]
	v_cndmask_b32_e64 v157, v157, v149, s[48:49]
	v_cndmask_b32_e64 v158, v158, v150, s[48:49]
	v_cndmask_b32_e64 v159, v159, v151, s[48:49]
	v_cvt_pk_bf16_f32 v160, v152, v153
	v_cvt_pk_bf16_f32 v161, v154, v155
	v_cvt_pk_bf16_f32 v162, v156, v157
	v_cvt_pk_bf16_f32 v163, v158, v159
	ds_write_b128 v6, v[160:163] offset:112
	s_waitcnt lgkmcnt(0)
	ds_read_b128 v[184:187], v14 offset:0
	ds_read_b128 v[188:191], v14 offset:64
	ds_read_b128 v[192:195], v14 offset:128
	ds_read_b128 v[196:199], v14 offset:192
	ds_read_b128 v[200:203], v14 offset:256
	ds_read_b128 v[204:207], v14 offset:320
	ds_read_b128 v[208:211], v14 offset:384
	ds_read_b128 v[212:215], v14 offset:448
	s_lshl_b32 s2, s26, 4
	v_add_u32_e32 v137, s2, v10
	v_lshl_add_u32 v132, v11, 4, v10
	v_lshlrev_b32_e32 v132, 4, v132
	v_mov_b32_e32 v133, v132
	v_lshlrev_b32_e32 v134, 4, v11
	s_lshl_b32 s2, s26, 4
	v_lshl_add_u32 v0, v11, 4, v10
	v_lshrrev_b32_e32 v135, 2, v0
	v_add_u32_e32 v135, s2, v135
	v_lshlrev_b32_e32 v135, 11, v135
	v_and_b32_e32 v136, 3, v0
	v_lshl_add_u32 v135, v136, 4, v135
	v_and_b32_e32 v136, 31, v0
	v_lshrrev_b32_e32 v136, 1, v136
	v_add_u32_e32 v136, s2, v136
	v_lshlrev_b32_e32 v136, 10, v136
	v_and_b32_e32 v128, 1, v0
	v_lshl_add_u32 v136, v128, 4, v136
	v_mov_b32_e32 v128, 0x1040000
	v_cmp_lt_u32_e32 vcc, 31, v0
	s_nop 1
	v_cndmask_b32_e32 v128, 0, v128, vcc
	v_add_u32_e32 v136, v128, v136
	s_mul_i32 s2, s27, 0x2100
	v_lshlrev_b32_e32 v128, 6, v10
	v_lshl_add_u32 v128, v11, 4, v128
	v_add_u32_e32 v128, s2, v128
	v_lshlrev_b32_e32 v129, 5, v10
	v_lshl_add_u32 v129, v11, 3, v129
	v_add_u32_e32 v129, s2, v129
	v_lshl_add_u32 v130, v0, 4, s2
	s_cmp_lg_u32 s57, 0
	s_cbranch_scc1 .Llora_single
	s_lshl_b32 s2, s56, 15
	v_add_u32_e32 v132, s2, v132
	s_lshl_b32 s2, s56, 16
	v_add_u32_e32 v133, s2, v133
	s_lshl_b32 s2, s56, 10
	v_add_u32_e32 v134, s2, v134
	v_add_u32_e32 v135, s2, v135
	s_lshl_b32 s2, s56, 9
	v_add_u32_e32 v136, s2, v136
	s_and_b32 s60, s27, 3
	s_cmp_gt_u32 s60, 1
	s_cselect_b32 s3, 1, 0
	s_movk_i32 s64, 0x800
	s_lshl_b32 s64, s64, s3
	s_lshl_b32 s2, s60, 16
	s_cmp_eq_u32 s60, 2
	s_cselect_b32 s2, 0x20000, s2
	s_cmp_eq_u32 s60, 3
	s_cselect_b32 s2, 0x20800, s2
	s_lshl_b32 s3, s64, 4
	s_mul_i32 s3, s3, s56
	s_add_u32 s2, s2, s3
	s_add_u32 s62, s24, s2
	s_addc_u32 s63, s25, 0
	s_lshl_b32 s2, s56, 13
	s_lshl_b32 s3, s60, 11
	s_add_i32 s2, s2, s3
	s_add_i32 s60, s2, 0x10800
	v_lshl_add_u32 v138, v11, 4, v10
	v_lshlrev_b32_e32 v138, 4, v138
	v_add_u32_e32 v139, 0x400, v138
	v_add_u32_e32 v144, s60, v138
	s_lshl_b32 s2, s56, 13
	v_add_u32_e32 v140, s2, v138
	v_add_u32_e32 v140, 0x10800, v140
	v_lshlrev_b32_e32 v141, 2, v180
	global_load_dword v142, v141, s[20:21]
	global_load_dword v143, v141, s[22:23]
	v_add_u32_e32 v134, 0x1c800, v134
	v_add_u32_e32 v141, 0x1c800, v141
	global_load_dwordx4 v[56:59], v138, s[62:63]
	global_load_dwordx4 v[60:63], v139, s[62:63]
	s_add_u32 s62, s62, s64
	s_addc_u32 s63, s63, 0
	global_load_dwordx4 v[64:67], v138, s[62:63]
	global_load_dwordx4 v[68:71], v139, s[62:63]
	s_add_u32 s62, s62, s64
	s_addc_u32 s63, s63, 0
	s_waitcnt vmcnt(4)
	ds_write_b32 v141, v142
	ds_write_b32 v141, v143 offset:2048
	s_waitcnt vmcnt(2)
	ds_write_b128 v144, v[56:59] offset:0
	ds_write_b128 v144, v[60:63] offset:1024
	s_waitcnt lgkmcnt(0)
	s_barrier
; __device__ __forceinline__ unsigned pk2(float lo, float hi) { f32x2 v = {lo, hi}; bf16x2_t b = __builtin_convertvector(v, bf16x2_t); return __builtin_bit_cast(unsigned, b); }
; __device__ __forceinline__ float sigmoidf_(float x) { return frcp(1.f + fexp2(-1.4426950408889634f * x)); }
; __device__ __forceinline__ void phase_lora(const Ctx& p, LAS unsigned char* lds) {
;     ...
;         auto tile = [&](const WF& f, int nt) {
;             f32x4 aw = (f32x4){0.f, 0.f, 0.f, 0.f}, aa = aw, ag = aw;
; #pragma unroll
;             for (int ks = 0; ks < 2; ++ks) { aw = __builtin_amdgcn_mfma_f32_16x16x32_bf16(f.w[ks], bx[ks], aw, 0, 0, 0); aa = __builtin_amdgcn_mfma_f32_16x16x32_bf16(f.a[ks], bx[2 + ks], aa, 0, 0, 0); }
; #pragma unroll
;             for (int ks = 0; ks < 4; ++ks) ag = __builtin_amdgcn_mfma_f32_16x16x32_bf16(f.gq[ks], bx[4 + ks], ag, 0, 0, 0);
;             const int c = nt * 16 + 4 * g;
;             f32x4 dec; float av[4];
; #pragma unroll
;             for (int e = 0; e < 4; ++e) {
;                 const float x = f.w0[e] + aw[e];
;                 const float sp = fmaxf(-x, 0.f) + log1pf(expf(-fabsf(x)));
;                 dec[e] = expf(-expf(-sp - 0.5f));
;                 av[e] = sigmoidf_(f.a0[e] + aa[e]);
;             }
;             *(f32x4*)(DEC + (size_t)row * 512 + c) = dec;
;             *(u32x2*)(AB + (size_t)row * 512 + c) = (u32x2){pk2(av[0], av[1]), pk2(av[2], av[3])};
;             *(u32x2*)(GG + (size_t)row * 512 + c) = (u32x2){pk2(ag[0], ag[1]), pk2(ag[2], ag[3])};
;         };
;         WF fa, fb;
;         ldw(fa, 0);
; #pragma unroll 1
;         for (int nt = 0; nt < 32; nt += 2) {
;             ldw(fb, nt + 1);
;             tile(fa, nt);
;             ldw(fa, (nt + 2) & 31);
;             tile(fb, nt + 1);
	ds_read_b128 v[16:19], v140 offset:0
	ds_read_b128 v[20:23], v140 offset:1024
	ds_read_b128 v[24:27], v140 offset:2048
	ds_read_b128 v[28:31], v140 offset:3072
	ds_read_b128 v[32:35], v140 offset:4096
	ds_read_b128 v[36:39], v140 offset:5120
	ds_read_b128 v[40:43], v140 offset:6144
	ds_read_b128 v[44:47], v140 offset:7168
	ds_read_b128 v[48:51], v134
	ds_read_b128 v[52:55], v134 offset:2048
	v_add_u32_e32 v134, 64, v134
	s_waitcnt vmcnt(0)
	ds_write_b128 v144, v[64:67] offset:16384
	ds_write_b128 v144, v[68:71] offset:17408
	global_load_dwordx4 v[56:59], v138, s[62:63]
	global_load_dwordx4 v[60:63], v139, s[62:63]
	s_add_u32 s62, s62, s64
	s_addc_u32 s63, s63, 0
	s_waitcnt lgkmcnt(0)
	v_mfma_f32_16x16x32_bf16 v[96:99], v[16:19], v[184:187], 0
	v_mfma_f32_16x16x32_bf16 v[100:103], v[24:27], v[192:195], 0
	v_mfma_f32_16x16x32_bf16 v[104:107], v[32:35], v[200:203], 0
	v_mfma_f32_16x16x32_bf16 v[96:99], v[20:23], v[188:191], v[96:99]
	v_mfma_f32_16x16x32_bf16 v[100:103], v[28:31], v[196:199], v[100:103]
	v_mfma_f32_16x16x32_bf16 v[104:107], v[36:39], v[204:207], v[104:107]
	v_mfma_f32_16x16x32_bf16 v[104:107], v[40:43], v[208:211], v[104:107]
	v_mfma_f32_16x16x32_bf16 v[104:107], v[44:47], v[212:215], v[104:107]
	s_nop 4
	v_add_f32_e32 v108, v48, v96
	v_add_f32_e32 v109, v49, v97
	v_add_f32_e32 v110, v50, v98
	v_add_f32_e32 v111, v51, v99
	v_add_f32_e32 v112, v52, v100
	v_add_f32_e32 v113, v53, v101
	v_add_f32_e32 v114, v54, v102
	v_add_f32_e32 v115, v55, v103
	v_mul_f32_e32 v108, 0xbfb8aa3b, v108
	v_mul_f32_e32 v109, 0xbfb8aa3b, v109
	v_mul_f32_e32 v110, 0xbfb8aa3b, v110
	v_mul_f32_e32 v111, 0xbfb8aa3b, v111
	v_mul_f32_e32 v112, 0xbfb8aa3b, v112
	v_mul_f32_e32 v113, 0xbfb8aa3b, v113
	v_mul_f32_e32 v114, 0xbfb8aa3b, v114
	v_mul_f32_e32 v115, 0xbfb8aa3b, v115
	v_exp_f32_e32 v108, v108
	v_exp_f32_e32 v109, v109
	v_exp_f32_e32 v110, v110
	v_exp_f32_e32 v111, v111
	v_exp_f32_e32 v112, v112
	v_exp_f32_e32 v113, v113
	v_exp_f32_e32 v114, v114
	v_exp_f32_e32 v115, v115
	v_add_f32_e32 v108, 1.0, v108
	v_add_f32_e32 v109, 1.0, v109
	v_add_f32_e32 v110, 1.0, v110
	v_add_f32_e32 v111, 1.0, v111
	v_add_f32_e32 v112, 1.0, v112
	v_add_f32_e32 v113, 1.0, v113
	v_add_f32_e32 v114, 1.0, v114
	v_add_f32_e32 v115, 1.0, v115
	v_rcp_f32_e32 v108, v108
	v_rcp_f32_e32 v109, v109
	v_rcp_f32_e32 v110, v110
	v_rcp_f32_e32 v111, v111
	v_rcp_f32_e32 v112, v112
	v_rcp_f32_e32 v113, v113
	v_rcp_f32_e32 v114, v114
	v_rcp_f32_e32 v115, v115
	v_mul_f32_e32 v108, 0xbf60028b, v108
	v_mul_f32_e32 v109, 0xbf60028b, v109
	v_mul_f32_e32 v110, 0xbf60028b, v110
	v_mul_f32_e32 v111, 0xbf60028b, v111
	v_cvt_pk_bf16_f32 v116, v112, v113
	v_cvt_pk_bf16_f32 v117, v114, v115
	v_exp_f32_e32 v108, v108
	v_exp_f32_e32 v109, v109
	v_exp_f32_e32 v110, v110
	v_exp_f32_e32 v111, v111
	v_cvt_pk_bf16_f32 v118, v104, v105
	v_cvt_pk_bf16_f32 v119, v106, v107
	ds_write_b128 v128, v[108:111]
	ds_write_b64 v129, v[116:117] offset:1024
	ds_write_b64 v129, v[118:119] offset:1536
	s_waitcnt lgkmcnt(0)
	ds_read_b128 v[120:123], v130
	ds_read_b128 v[124:127], v130 offset:1024
	s_waitcnt lgkmcnt(0)
	global_store_dwordx4 v136, v[124:127], s[44:45]
	global_store_dwordx4 v135, v[120:123], s[54:55]
	v_add_u32_e32 v136, 32, v136
	v_add_u32_e32 v135, 64, v135
	s_barrier
	s_mov_b32 s61, 6
.Llora_roll:
	ds_read_b128 v[16:19], v140 offset:16384
	ds_read_b128 v[20:23], v140 offset:17408
	ds_read_b128 v[24:27], v140 offset:18432
	ds_read_b128 v[28:31], v140 offset:19456
	ds_read_b128 v[32:35], v140 offset:20480
	ds_read_b128 v[36:39], v140 offset:21504
	ds_read_b128 v[40:43], v140 offset:22528
	ds_read_b128 v[44:47], v140 offset:23552
	ds_read_b128 v[88:91], v134
	ds_read_b128 v[92:95], v134 offset:2048
	v_add_u32_e32 v134, 64, v134
	s_waitcnt vmcnt(2)
	ds_write_b128 v144, v[56:59] offset:0
	ds_write_b128 v144, v[60:63] offset:1024
	global_load_dwordx4 v[64:67], v138, s[62:63]
	global_load_dwordx4 v[68:71], v139, s[62:63]
	s_add_u32 s62, s62, s64
	s_addc_u32 s63, s63, 0
	s_waitcnt lgkmcnt(0)
	v_mfma_f32_16x16x32_bf16 v[96:99], v[16:19], v[184:187], 0
	v_mfma_f32_16x16x32_bf16 v[100:103], v[24:27], v[192:195], 0
	v_mfma_f32_16x16x32_bf16 v[104:107], v[32:35], v[200:203], 0
	v_mfma_f32_16x16x32_bf16 v[96:99], v[20:23], v[188:191], v[96:99]
	v_mfma_f32_16x16x32_bf16 v[100:103], v[28:31], v[196:199], v[100:103]
	v_mfma_f32_16x16x32_bf16 v[104:107], v[36:39], v[204:207], v[104:107]
	v_mfma_f32_16x16x32_bf16 v[104:107], v[40:43], v[208:211], v[104:107]
	v_mfma_f32_16x16x32_bf16 v[104:107], v[44:47], v[212:215], v[104:107]
	s_nop 4
	v_add_f32_e32 v108, v88, v96
	v_add_f32_e32 v109, v89, v97
	v_add_f32_e32 v110, v90, v98
	v_add_f32_e32 v111, v91, v99
	v_add_f32_e32 v112, v92, v100
	v_add_f32_e32 v113, v93, v101
	v_add_f32_e32 v114, v94, v102
	v_add_f32_e32 v115, v95, v103
	v_mul_f32_e32 v108, 0xbfb8aa3b, v108
	v_mul_f32_e32 v109, 0xbfb8aa3b, v109
	v_mul_f32_e32 v110, 0xbfb8aa3b, v110
	v_mul_f32_e32 v111, 0xbfb8aa3b, v111
	v_mul_f32_e32 v112, 0xbfb8aa3b, v112
	v_mul_f32_e32 v113, 0xbfb8aa3b, v113
	v_mul_f32_e32 v114, 0xbfb8aa3b, v114
	v_mul_f32_e32 v115, 0xbfb8aa3b, v115
	v_exp_f32_e32 v108, v108
	v_exp_f32_e32 v109, v109
	v_exp_f32_e32 v110, v110
	v_exp_f32_e32 v111, v111
	v_exp_f32_e32 v112, v112
	v_exp_f32_e32 v113, v113
	v_exp_f32_e32 v114, v114
	v_exp_f32_e32 v115, v115
	v_add_f32_e32 v108, 1.0, v108
	v_add_f32_e32 v109, 1.0, v109
	v_add_f32_e32 v110, 1.0, v110
	v_add_f32_e32 v111, 1.0, v111
	v_add_f32_e32 v112, 1.0, v112
	v_add_f32_e32 v113, 1.0, v113
	v_add_f32_e32 v114, 1.0, v114
	v_add_f32_e32 v115, 1.0, v115
	v_rcp_f32_e32 v108, v108
	v_rcp_f32_e32 v109, v109
	v_rcp_f32_e32 v110, v110
	v_rcp_f32_e32 v111, v111
	v_rcp_f32_e32 v112, v112
	v_rcp_f32_e32 v113, v113
	v_rcp_f32_e32 v114, v114
	v_rcp_f32_e32 v115, v115
	v_mul_f32_e32 v108, 0xbf60028b, v108
	v_mul_f32_e32 v109, 0xbf60028b, v109
	v_mul_f32_e32 v110, 0xbf60028b, v110
	v_mul_f32_e32 v111, 0xbf60028b, v111
	v_cvt_pk_bf16_f32 v116, v112, v113
	v_cvt_pk_bf16_f32 v117, v114, v115
	v_exp_f32_e32 v108, v108
	v_exp_f32_e32 v109, v109
	v_exp_f32_e32 v110, v110
	v_exp_f32_e32 v111, v111
	v_cvt_pk_bf16_f32 v118, v104, v105
	v_cvt_pk_bf16_f32 v119, v106, v107
	ds_write_b128 v128, v[108:111]
	ds_write_b64 v129, v[116:117] offset:1024
	ds_write_b64 v129, v[118:119] offset:1536
	s_waitcnt lgkmcnt(0)
	ds_read_b128 v[120:123], v130
	ds_read_b128 v[124:127], v130 offset:1024
	s_waitcnt lgkmcnt(0)
	global_store_dwordx4 v136, v[124:127], s[44:45]
	global_store_dwordx4 v135, v[120:123], s[54:55]
	v_add_u32_e32 v136, 32, v136
	v_add_u32_e32 v135, 64, v135
	s_barrier
; __device__ __forceinline__ unsigned pk2(float lo, float hi) { f32x2 v = {lo, hi}; bf16x2_t b = __builtin_convertvector(v, bf16x2_t); return __builtin_bit_cast(unsigned, b); }
; __device__ __forceinline__ float sigmoidf_(float x) { return frcp(1.f + fexp2(-1.4426950408889634f * x)); }
; __device__ __forceinline__ void phase_lora(const Ctx& p, LAS unsigned char* lds) {
;     ...
;         auto tile = [&](const WF& f, int nt) {
;             f32x4 aw = (f32x4){0.f, 0.f, 0.f, 0.f}, aa = aw, ag = aw;
; #pragma unroll
;             for (int ks = 0; ks < 2; ++ks) { aw = __builtin_amdgcn_mfma_f32_16x16x32_bf16(f.w[ks], bx[ks], aw, 0, 0, 0); aa = __builtin_amdgcn_mfma_f32_16x16x32_bf16(f.a[ks], bx[2 + ks], aa, 0, 0, 0); }
; #pragma unroll
;             for (int ks = 0; ks < 4; ++ks) ag = __builtin_amdgcn_mfma_f32_16x16x32_bf16(f.gq[ks], bx[4 + ks], ag, 0, 0, 0);
;             const int c = nt * 16 + 4 * g;
;             f32x4 dec; float av[4];
; #pragma unroll
;             for (int e = 0; e < 4; ++e) {
;                 const float x = f.w0[e] + aw[e];
;                 const float sp = fmaxf(-x, 0.f) + log1pf(expf(-fabsf(x)));
;                 dec[e] = expf(-expf(-sp - 0.5f));
;                 av[e] = sigmoidf_(f.a0[e] + aa[e]);
;             }
;             *(f32x4*)(DEC + (size_t)row * 512 + c) = dec;
;             *(u32x2*)(AB + (size_t)row * 512 + c) = (u32x2){pk2(av[0], av[1]), pk2(av[2], av[3])};
;             *(u32x2*)(GG + (size_t)row * 512 + c) = (u32x2){pk2(ag[0], ag[1]), pk2(ag[2], ag[3])};
;         };
;         WF fa, fb;
;         ldw(fa, 0);
; #pragma unroll 1
;         for (int nt = 0; nt < 32; nt += 2) {
;             ldw(fb, nt + 1);
;             tile(fa, nt);
;             ldw(fa, (nt + 2) & 31);
;             tile(fb, nt + 1);
	ds_read_b128 v[16:19], v140 offset:0
	ds_read_b128 v[20:23], v140 offset:1024
	ds_read_b128 v[24:27], v140 offset:2048
	ds_read_b128 v[28:31], v140 offset:3072
	ds_read_b128 v[32:35], v140 offset:4096
	ds_read_b128 v[36:39], v140 offset:5120
	ds_read_b128 v[40:43], v140 offset:6144
	ds_read_b128 v[44:47], v140 offset:7168
	ds_read_b128 v[48:51], v134
	ds_read_b128 v[52:55], v134 offset:2048
	v_add_u32_e32 v134, 64, v134
	s_waitcnt vmcnt(2)
	ds_write_b128 v144, v[64:67] offset:16384
	ds_write_b128 v144, v[68:71] offset:17408
	global_load_dwordx4 v[56:59], v138, s[62:63]
	global_load_dwordx4 v[60:63], v139, s[62:63]
	s_add_u32 s62, s62, s64
	s_addc_u32 s63, s63, 0
	s_waitcnt lgkmcnt(0)
	v_mfma_f32_16x16x32_bf16 v[96:99], v[16:19], v[184:187], 0
	v_mfma_f32_16x16x32_bf16 v[100:103], v[24:27], v[192:195], 0
	v_mfma_f32_16x16x32_bf16 v[104:107], v[32:35], v[200:203], 0
	v_mfma_f32_16x16x32_bf16 v[96:99], v[20:23], v[188:191], v[96:99]
	v_mfma_f32_16x16x32_bf16 v[100:103], v[28:31], v[196:199], v[100:103]
	v_mfma_f32_16x16x32_bf16 v[104:107], v[36:39], v[204:207], v[104:107]
	v_mfma_f32_16x16x32_bf16 v[104:107], v[40:43], v[208:211], v[104:107]
	v_mfma_f32_16x16x32_bf16 v[104:107], v[44:47], v[212:215], v[104:107]
	s_nop 4
	v_add_f32_e32 v108, v48, v96
	v_add_f32_e32 v109, v49, v97
	v_add_f32_e32 v110, v50, v98
	v_add_f32_e32 v111, v51, v99
	v_add_f32_e32 v112, v52, v100
	v_add_f32_e32 v113, v53, v101
	v_add_f32_e32 v114, v54, v102
	v_add_f32_e32 v115, v55, v103
	v_mul_f32_e32 v108, 0xbfb8aa3b, v108
	v_mul_f32_e32 v109, 0xbfb8aa3b, v109
	v_mul_f32_e32 v110, 0xbfb8aa3b, v110
	v_mul_f32_e32 v111, 0xbfb8aa3b, v111
	v_mul_f32_e32 v112, 0xbfb8aa3b, v112
	v_mul_f32_e32 v113, 0xbfb8aa3b, v113
	v_mul_f32_e32 v114, 0xbfb8aa3b, v114
	v_mul_f32_e32 v115, 0xbfb8aa3b, v115
	v_exp_f32_e32 v108, v108
	v_exp_f32_e32 v109, v109
	v_exp_f32_e32 v110, v110
	v_exp_f32_e32 v111, v111
	v_exp_f32_e32 v112, v112
	v_exp_f32_e32 v113, v113
	v_exp_f32_e32 v114, v114
	v_exp_f32_e32 v115, v115
	v_add_f32_e32 v108, 1.0, v108
	v_add_f32_e32 v109, 1.0, v109
	v_add_f32_e32 v110, 1.0, v110
	v_add_f32_e32 v111, 1.0, v111
	v_add_f32_e32 v112, 1.0, v112
	v_add_f32_e32 v113, 1.0, v113
	v_add_f32_e32 v114, 1.0, v114
	v_add_f32_e32 v115, 1.0, v115
	v_rcp_f32_e32 v108, v108
	v_rcp_f32_e32 v109, v109
	v_rcp_f32_e32 v110, v110
	v_rcp_f32_e32 v111, v111
	v_rcp_f32_e32 v112, v112
	v_rcp_f32_e32 v113, v113
	v_rcp_f32_e32 v114, v114
	v_rcp_f32_e32 v115, v115
	v_mul_f32_e32 v108, 0xbf60028b, v108
	v_mul_f32_e32 v109, 0xbf60028b, v109
	v_mul_f32_e32 v110, 0xbf60028b, v110
	v_mul_f32_e32 v111, 0xbf60028b, v111
	v_cvt_pk_bf16_f32 v116, v112, v113
	v_cvt_pk_bf16_f32 v117, v114, v115
	v_exp_f32_e32 v108, v108
	v_exp_f32_e32 v109, v109
	v_exp_f32_e32 v110, v110
	v_exp_f32_e32 v111, v111
	v_cvt_pk_bf16_f32 v118, v104, v105
	v_cvt_pk_bf16_f32 v119, v106, v107
	ds_write_b128 v128, v[108:111]
	ds_write_b64 v129, v[116:117] offset:1024
	ds_write_b64 v129, v[118:119] offset:1536
	s_waitcnt lgkmcnt(0)
	ds_read_b128 v[120:123], v130
	ds_read_b128 v[124:127], v130 offset:1024
	s_waitcnt lgkmcnt(0)
	global_store_dwordx4 v136, v[124:127], s[44:45]
	global_store_dwordx4 v135, v[120:123], s[54:55]
	v_add_u32_e32 v136, 32, v136
	v_add_u32_e32 v135, 64, v135
	s_barrier
	s_sub_u32 s61, s61, 1
	s_cmp_lg_u32 s61, 0
	s_cbranch_scc1 .Llora_roll
	ds_read_b128 v[16:19], v140 offset:16384
	ds_read_b128 v[20:23], v140 offset:17408
	ds_read_b128 v[24:27], v140 offset:18432
	ds_read_b128 v[28:31], v140 offset:19456
	ds_read_b128 v[32:35], v140 offset:20480
	ds_read_b128 v[36:39], v140 offset:21504
	ds_read_b128 v[40:43], v140 offset:22528
	ds_read_b128 v[44:47], v140 offset:23552
	ds_read_b128 v[88:91], v134
	ds_read_b128 v[92:95], v134 offset:2048
	v_add_u32_e32 v134, 64, v134
	s_waitcnt vmcnt(2)
	ds_write_b128 v144, v[56:59] offset:0
	ds_write_b128 v144, v[60:63] offset:1024
	global_load_dwordx4 v[64:67], v138, s[62:63]
	global_load_dwordx4 v[68:71], v139, s[62:63]
	s_add_u32 s62, s62, s64
	s_addc_u32 s63, s63, 0
	s_waitcnt lgkmcnt(0)
	v_mfma_f32_16x16x32_bf16 v[96:99], v[16:19], v[184:187], 0
	v_mfma_f32_16x16x32_bf16 v[100:103], v[24:27], v[192:195], 0
	v_mfma_f32_16x16x32_bf16 v[104:107], v[32:35], v[200:203], 0
	v_mfma_f32_16x16x32_bf16 v[96:99], v[20:23], v[188:191], v[96:99]
	v_mfma_f32_16x16x32_bf16 v[100:103], v[28:31], v[196:199], v[100:103]
	v_mfma_f32_16x16x32_bf16 v[104:107], v[36:39], v[204:207], v[104:107]
	v_mfma_f32_16x16x32_bf16 v[104:107], v[40:43], v[208:211], v[104:107]
	v_mfma_f32_16x16x32_bf16 v[104:107], v[44:47], v[212:215], v[104:107]
	s_nop 4
	v_add_f32_e32 v108, v88, v96
	v_add_f32_e32 v109, v89, v97
	v_add_f32_e32 v110, v90, v98
	v_add_f32_e32 v111, v91, v99
	v_add_f32_e32 v112, v92, v100
	v_add_f32_e32 v113, v93, v101
	v_add_f32_e32 v114, v94, v102
	v_add_f32_e32 v115, v95, v103
	v_mul_f32_e32 v108, 0xbfb8aa3b, v108
	v_mul_f32_e32 v109, 0xbfb8aa3b, v109
	v_mul_f32_e32 v110, 0xbfb8aa3b, v110
	v_mul_f32_e32 v111, 0xbfb8aa3b, v111
	v_mul_f32_e32 v112, 0xbfb8aa3b, v112
	v_mul_f32_e32 v113, 0xbfb8aa3b, v113
	v_mul_f32_e32 v114, 0xbfb8aa3b, v114
	v_mul_f32_e32 v115, 0xbfb8aa3b, v115
	v_exp_f32_e32 v108, v108
	v_exp_f32_e32 v109, v109
	v_exp_f32_e32 v110, v110
	v_exp_f32_e32 v111, v111
	v_exp_f32_e32 v112, v112
	v_exp_f32_e32 v113, v113
	v_exp_f32_e32 v114, v114
	v_exp_f32_e32 v115, v115
	v_add_f32_e32 v108, 1.0, v108
	v_add_f32_e32 v109, 1.0, v109
	v_add_f32_e32 v110, 1.0, v110
	v_add_f32_e32 v111, 1.0, v111
	v_add_f32_e32 v112, 1.0, v112
	v_add_f32_e32 v113, 1.0, v113
	v_add_f32_e32 v114, 1.0, v114
	v_add_f32_e32 v115, 1.0, v115
	v_rcp_f32_e32 v108, v108
	v_rcp_f32_e32 v109, v109
	v_rcp_f32_e32 v110, v110
	v_rcp_f32_e32 v111, v111
	v_rcp_f32_e32 v112, v112
	v_rcp_f32_e32 v113, v113
	v_rcp_f32_e32 v114, v114
	v_rcp_f32_e32 v115, v115
	v_mul_f32_e32 v108, 0xbf60028b, v108
	v_mul_f32_e32 v109, 0xbf60028b, v109
	v_mul_f32_e32 v110, 0xbf60028b, v110
	v_mul_f32_e32 v111, 0xbf60028b, v111
	v_cvt_pk_bf16_f32 v116, v112, v113
	v_cvt_pk_bf16_f32 v117, v114, v115
	v_exp_f32_e32 v108, v108
	v_exp_f32_e32 v109, v109
	v_exp_f32_e32 v110, v110
	v_exp_f32_e32 v111, v111
	v_cvt_pk_bf16_f32 v118, v104, v105
	v_cvt_pk_bf16_f32 v119, v106, v107
	ds_write_b128 v128, v[108:111]
	ds_write_b64 v129, v[116:117] offset:1024
	ds_write_b64 v129, v[118:119] offset:1536
	s_waitcnt lgkmcnt(0)
	ds_read_b128 v[120:123], v130
	ds_read_b128 v[124:127], v130 offset:1024
	s_waitcnt lgkmcnt(0)
	global_store_dwordx4 v136, v[124:127], s[44:45]
	global_store_dwordx4 v135, v[120:123], s[54:55]
	v_add_u32_e32 v136, 32, v136
	v_add_u32_e32 v135, 64, v135
	s_barrier
; __device__ __forceinline__ unsigned pk2(float lo, float hi) { f32x2 v = {lo, hi}; bf16x2_t b = __builtin_convertvector(v, bf16x2_t); return __builtin_bit_cast(unsigned, b); }
; __device__ __forceinline__ float sigmoidf_(float x) { return frcp(1.f + fexp2(-1.4426950408889634f * x)); }
; __device__ __forceinline__ void phase_lora(const Ctx& p, LAS unsigned char* lds) {
;     ...
;         auto tile = [&](const WF& f, int nt) {
;             f32x4 aw = (f32x4){0.f, 0.f, 0.f, 0.f}, aa = aw, ag = aw;
; #pragma unroll
;             for (int ks = 0; ks < 2; ++ks) { aw = __builtin_amdgcn_mfma_f32_16x16x32_bf16(f.w[ks], bx[ks], aw, 0, 0, 0); aa = __builtin_amdgcn_mfma_f32_16x16x32_bf16(f.a[ks], bx[2 + ks], aa, 0, 0, 0); }
; #pragma unroll
;             for (int ks = 0; ks < 4; ++ks) ag = __builtin_amdgcn_mfma_f32_16x16x32_bf16(f.gq[ks], bx[4 + ks], ag, 0, 0, 0);
;             const int c = nt * 16 + 4 * g;
;             f32x4 dec; float av[4];
; #pragma unroll
;             for (int e = 0; e < 4; ++e) {
;                 const float x = f.w0[e] + aw[e];
;                 const float sp = fmaxf(-x, 0.f) + log1pf(expf(-fabsf(x)));
;                 dec[e] = expf(-expf(-sp - 0.5f));
;                 av[e] = sigmoidf_(f.a0[e] + aa[e]);
;             }
;             *(f32x4*)(DEC + (size_t)row * 512 + c) = dec;
;             *(u32x2*)(AB + (size_t)row * 512 + c) = (u32x2){pk2(av[0], av[1]), pk2(av[2], av[3])};
;             *(u32x2*)(GG + (size_t)row * 512 + c) = (u32x2){pk2(ag[0], ag[1]), pk2(ag[2], ag[3])};
;         };
;         WF fa, fb;
;         ldw(fa, 0);
; #pragma unroll 1
;         for (int nt = 0; nt < 32; nt += 2) {
;             ldw(fb, nt + 1);
;             tile(fa, nt);
;             ldw(fa, (nt + 2) & 31);
;             tile(fb, nt + 1);
;         }
	ds_read_b128 v[16:19], v140 offset:0
	ds_read_b128 v[20:23], v140 offset:1024
	ds_read_b128 v[24:27], v140 offset:2048
	ds_read_b128 v[28:31], v140 offset:3072
	ds_read_b128 v[32:35], v140 offset:4096
	ds_read_b128 v[36:39], v140 offset:5120
	ds_read_b128 v[40:43], v140 offset:6144
	ds_read_b128 v[44:47], v140 offset:7168
	ds_read_b128 v[48:51], v134
	ds_read_b128 v[52:55], v134 offset:2048
	v_add_u32_e32 v134, 64, v134
	s_waitcnt vmcnt(2)
	ds_write_b128 v144, v[64:67] offset:16384
	ds_write_b128 v144, v[68:71] offset:17408
	s_waitcnt lgkmcnt(0)
	v_mfma_f32_16x16x32_bf16 v[96:99], v[16:19], v[184:187], 0
	v_mfma_f32_16x16x32_bf16 v[100:103], v[24:27], v[192:195], 0
	v_mfma_f32_16x16x32_bf16 v[104:107], v[32:35], v[200:203], 0
	v_mfma_f32_16x16x32_bf16 v[96:99], v[20:23], v[188:191], v[96:99]
	v_mfma_f32_16x16x32_bf16 v[100:103], v[28:31], v[196:199], v[100:103]
	v_mfma_f32_16x16x32_bf16 v[104:107], v[36:39], v[204:207], v[104:107]
	v_mfma_f32_16x16x32_bf16 v[104:107], v[40:43], v[208:211], v[104:107]
	v_mfma_f32_16x16x32_bf16 v[104:107], v[44:47], v[212:215], v[104:107]
	s_nop 4
	v_add_f32_e32 v108, v48, v96
	v_add_f32_e32 v109, v49, v97
	v_add_f32_e32 v110, v50, v98
	v_add_f32_e32 v111, v51, v99
	v_add_f32_e32 v112, v52, v100
	v_add_f32_e32 v113, v53, v101
	v_add_f32_e32 v114, v54, v102
	v_add_f32_e32 v115, v55, v103
	v_mul_f32_e32 v108, 0xbfb8aa3b, v108
	v_mul_f32_e32 v109, 0xbfb8aa3b, v109
	v_mul_f32_e32 v110, 0xbfb8aa3b, v110
	v_mul_f32_e32 v111, 0xbfb8aa3b, v111
	v_mul_f32_e32 v112, 0xbfb8aa3b, v112
	v_mul_f32_e32 v113, 0xbfb8aa3b, v113
	v_mul_f32_e32 v114, 0xbfb8aa3b, v114
	v_mul_f32_e32 v115, 0xbfb8aa3b, v115
	v_exp_f32_e32 v108, v108
	v_exp_f32_e32 v109, v109
	v_exp_f32_e32 v110, v110
	v_exp_f32_e32 v111, v111
	v_exp_f32_e32 v112, v112
	v_exp_f32_e32 v113, v113
	v_exp_f32_e32 v114, v114
	v_exp_f32_e32 v115, v115
	v_add_f32_e32 v108, 1.0, v108
	v_add_f32_e32 v109, 1.0, v109
	v_add_f32_e32 v110, 1.0, v110
	v_add_f32_e32 v111, 1.0, v111
	v_add_f32_e32 v112, 1.0, v112
	v_add_f32_e32 v113, 1.0, v113
	v_add_f32_e32 v114, 1.0, v114
	v_add_f32_e32 v115, 1.0, v115
	v_rcp_f32_e32 v108, v108
	v_rcp_f32_e32 v109, v109
	v_rcp_f32_e32 v110, v110
	v_rcp_f32_e32 v111, v111
	v_rcp_f32_e32 v112, v112
	v_rcp_f32_e32 v113, v113
	v_rcp_f32_e32 v114, v114
	v_rcp_f32_e32 v115, v115
	v_mul_f32_e32 v108, 0xbf60028b, v108
	v_mul_f32_e32 v109, 0xbf60028b, v109
	v_mul_f32_e32 v110, 0xbf60028b, v110
	v_mul_f32_e32 v111, 0xbf60028b, v111
	v_cvt_pk_bf16_f32 v116, v112, v113
	v_cvt_pk_bf16_f32 v117, v114, v115
	v_exp_f32_e32 v108, v108
	v_exp_f32_e32 v109, v109
	v_exp_f32_e32 v110, v110
	v_exp_f32_e32 v111, v111
	v_cvt_pk_bf16_f32 v118, v104, v105
	v_cvt_pk_bf16_f32 v119, v106, v107
	ds_write_b128 v128, v[108:111]
	ds_write_b64 v129, v[116:117] offset:1024
	ds_write_b64 v129, v[118:119] offset:1536
	s_waitcnt lgkmcnt(0)
	ds_read_b128 v[120:123], v130
	ds_read_b128 v[124:127], v130 offset:1024
	s_waitcnt lgkmcnt(0)
	global_store_dwordx4 v136, v[124:127], s[44:45]
	global_store_dwordx4 v135, v[120:123], s[54:55]
	v_add_u32_e32 v136, 32, v136
	v_add_u32_e32 v135, 64, v135
	s_barrier
	ds_read_b128 v[16:19], v140 offset:16384
	ds_read_b128 v[20:23], v140 offset:17408
	ds_read_b128 v[24:27], v140 offset:18432
	ds_read_b128 v[28:31], v140 offset:19456
	ds_read_b128 v[32:35], v140 offset:20480
	ds_read_b128 v[36:39], v140 offset:21504
	ds_read_b128 v[40:43], v140 offset:22528
	ds_read_b128 v[44:47], v140 offset:23552
	ds_read_b128 v[88:91], v134
	ds_read_b128 v[92:95], v134 offset:2048
	v_add_u32_e32 v134, 64, v134
	s_waitcnt lgkmcnt(0)
	v_mfma_f32_16x16x32_bf16 v[96:99], v[16:19], v[184:187], 0
	v_mfma_f32_16x16x32_bf16 v[100:103], v[24:27], v[192:195], 0
	v_mfma_f32_16x16x32_bf16 v[104:107], v[32:35], v[200:203], 0
	v_mfma_f32_16x16x32_bf16 v[96:99], v[20:23], v[188:191], v[96:99]
	v_mfma_f32_16x16x32_bf16 v[100:103], v[28:31], v[196:199], v[100:103]
	v_mfma_f32_16x16x32_bf16 v[104:107], v[36:39], v[204:207], v[104:107]
	v_mfma_f32_16x16x32_bf16 v[104:107], v[40:43], v[208:211], v[104:107]
	v_mfma_f32_16x16x32_bf16 v[104:107], v[44:47], v[212:215], v[104:107]
	s_nop 4
	v_add_f32_e32 v108, v88, v96
	v_add_f32_e32 v109, v89, v97
	v_add_f32_e32 v110, v90, v98
	v_add_f32_e32 v111, v91, v99
	v_add_f32_e32 v112, v92, v100
	v_add_f32_e32 v113, v93, v101
	v_add_f32_e32 v114, v94, v102
	v_add_f32_e32 v115, v95, v103
	v_mul_f32_e32 v108, 0xbfb8aa3b, v108
	v_mul_f32_e32 v109, 0xbfb8aa3b, v109
	v_mul_f32_e32 v110, 0xbfb8aa3b, v110
	v_mul_f32_e32 v111, 0xbfb8aa3b, v111
	v_mul_f32_e32 v112, 0xbfb8aa3b, v112
	v_mul_f32_e32 v113, 0xbfb8aa3b, v113
	v_mul_f32_e32 v114, 0xbfb8aa3b, v114
	v_mul_f32_e32 v115, 0xbfb8aa3b, v115
	v_exp_f32_e32 v108, v108
	v_exp_f32_e32 v109, v109
	v_exp_f32_e32 v110, v110
	v_exp_f32_e32 v111, v111
	v_exp_f32_e32 v112, v112
	v_exp_f32_e32 v113, v113
	v_exp_f32_e32 v114, v114
	v_exp_f32_e32 v115, v115
	v_add_f32_e32 v108, 1.0, v108
	v_add_f32_e32 v109, 1.0, v109
	v_add_f32_e32 v110, 1.0, v110
	v_add_f32_e32 v111, 1.0, v111
	v_add_f32_e32 v112, 1.0, v112
	v_add_f32_e32 v113, 1.0, v113
	v_add_f32_e32 v114, 1.0, v114
	v_add_f32_e32 v115, 1.0, v115
	v_rcp_f32_e32 v108, v108
	v_rcp_f32_e32 v109, v109
	v_rcp_f32_e32 v110, v110
	v_rcp_f32_e32 v111, v111
	v_rcp_f32_e32 v112, v112
	v_rcp_f32_e32 v113, v113
	v_rcp_f32_e32 v114, v114
	v_rcp_f32_e32 v115, v115
	v_mul_f32_e32 v108, 0xbf60028b, v108
	v_mul_f32_e32 v109, 0xbf60028b, v109
	v_mul_f32_e32 v110, 0xbf60028b, v110
	v_mul_f32_e32 v111, 0xbf60028b, v111
	v_cvt_pk_bf16_f32 v116, v112, v113
	v_cvt_pk_bf16_f32 v117, v114, v115
	v_exp_f32_e32 v108, v108
	v_exp_f32_e32 v109, v109
	v_exp_f32_e32 v110, v110
	v_exp_f32_e32 v111, v111
	v_cvt_pk_bf16_f32 v118, v104, v105
	v_cvt_pk_bf16_f32 v119, v106, v107
	ds_write_b128 v128, v[108:111]
	ds_write_b64 v129, v[116:117] offset:1024
	ds_write_b64 v129, v[118:119] offset:1536
	s_waitcnt lgkmcnt(0)
	ds_read_b128 v[120:123], v130
	ds_read_b128 v[124:127], v130 offset:1024
	s_waitcnt lgkmcnt(0)
	global_store_dwordx4 v136, v[124:127], s[44:45]
	global_store_dwordx4 v135, v[120:123], s[54:55]
	v_add_u32_e32 v136, 32, v136
	v_add_u32_e32 v135, 64, v135
	s_cmp_lt_u32 s28, 32
	s_cbranch_scc0 .Llora_done
	s_mov_b32 s57, 1
	s_lshr_b32 s2, s28, 2
	s_add_i32 s26, s2, 0x400
	s_branch .Llora_item
; __device__ __forceinline__ unsigned pk2(float lo, float hi) { f32x2 v = {lo, hi}; bf16x2_t b = __builtin_convertvector(v, bf16x2_t); return __builtin_bit_cast(unsigned, b); }
; __device__ __forceinline__ float sigmoidf_(float x) { return frcp(1.f + fexp2(-1.4426950408889634f * x)); }
;     __device__ __forceinline__ const float* in(int i) const { return (const float*)ptr(i); }
; __device__ __forceinline__ void phase_lora(const Ctx& p, LAS unsigned char* lds) {
;     ...
;         auto ldw = [&](WF& f, int nt) {
;             const int n = nt * 16 + q, c = nt * 16 + 4 * g;
; #pragma unroll
;             for (int ks = 0; ks < 2; ++ks) { f.w[ks] = *(const bf16x8*)(w2T + n * 64 + ks * 32 + 8 * g); f.a[ks] = *(const bf16x8*)(a2T + n * 64 + ks * 32 + 8 * g); }
; #pragma unroll
;             for (int ks = 0; ks < 4; ++ks) f.gq[ks] = *(const bf16x8*)(g2T + n * 128 + ks * 32 + 8 * g);
;             f.w0 = *(const f32x4*)(p.in(18) + c); f.a0 = *(const f32x4*)(p.in(20) + c);
;         };
;         auto tile = [&](const WF& f, int nt) {
;             f32x4 aw = (f32x4){0.f, 0.f, 0.f, 0.f}, aa = aw, ag = aw;
; #pragma unroll
;             for (int ks = 0; ks < 2; ++ks) { aw = __builtin_amdgcn_mfma_f32_16x16x32_bf16(f.w[ks], bx[ks], aw, 0, 0, 0); aa = __builtin_amdgcn_mfma_f32_16x16x32_bf16(f.a[ks], bx[2 + ks], aa, 0, 0, 0); }
; #pragma unroll
;             for (int ks = 0; ks < 4; ++ks) ag = __builtin_amdgcn_mfma_f32_16x16x32_bf16(f.gq[ks], bx[4 + ks], ag, 0, 0, 0);
;             const int c = nt * 16 + 4 * g;
;             f32x4 dec; float av[4];
; #pragma unroll
;             for (int e = 0; e < 4; ++e) {
;                 const float x = f.w0[e] + aw[e];
;                 const float sp = fmaxf(-x, 0.f) + log1pf(expf(-fabsf(x)));
;                 dec[e] = expf(-expf(-sp - 0.5f));
;                 av[e] = sigmoidf_(f.a0[e] + aa[e]);
;             }
;             *(f32x4*)(DEC + (size_t)row * 512 + c) = dec;
;             *(u32x2*)(AB + (size_t)row * 512 + c) = (u32x2){pk2(av[0], av[1]), pk2(av[2], av[3])};
;             *(u32x2*)(GG + (size_t)row * 512 + c) = (u32x2){pk2(ag[0], ag[1]), pk2(ag[2], ag[3])};
;         };
.Llora_single:
	s_and_b32 s2, s28, 3
	s_lshl_b32 s2, s2, 3
	s_add_i32 s2, s2, s27
	s_lshl_b32 s3, s2, 11
	v_add_u32_e32 v132, s3, v132
	s_lshl_b32 s3, s2, 12
	v_add_u32_e32 v133, s3, v133
	s_lshl_b32 s3, s2, 6
	v_add_u32_e32 v134, s3, v134
	v_add_u32_e32 v135, s3, v135
	s_lshl_b32 s3, s2, 5
	v_add_u32_e32 v136, s3, v136
	global_load_dwordx4 v[16:19], v132, s[24:25]
	global_load_dwordx4 v[20:23], v132, s[24:25] offset:1024
	global_load_dwordx4 v[24:27], v132, s[40:41]
	global_load_dwordx4 v[28:31], v132, s[40:41] offset:1024
	global_load_dwordx4 v[32:35], v133, s[42:43]
	global_load_dwordx4 v[36:39], v133, s[42:43] offset:1024
	global_load_dwordx4 v[40:43], v133, s[42:43] offset:2048
	global_load_dwordx4 v[44:47], v133, s[42:43] offset:3072
	global_load_dwordx4 v[48:51], v134, s[20:21]
	global_load_dwordx4 v[52:55], v134, s[22:23]
	s_waitcnt lgkmcnt(0)
	s_waitcnt vmcnt(0)
	v_mfma_f32_16x16x32_bf16 v[96:99], v[16:19], v[184:187], 0
	v_mfma_f32_16x16x32_bf16 v[100:103], v[24:27], v[192:195], 0
	v_mfma_f32_16x16x32_bf16 v[104:107], v[32:35], v[200:203], 0
	v_mfma_f32_16x16x32_bf16 v[96:99], v[20:23], v[188:191], v[96:99]
	v_mfma_f32_16x16x32_bf16 v[100:103], v[28:31], v[196:199], v[100:103]
	v_mfma_f32_16x16x32_bf16 v[104:107], v[36:39], v[204:207], v[104:107]
	v_mfma_f32_16x16x32_bf16 v[104:107], v[40:43], v[208:211], v[104:107]
	v_mfma_f32_16x16x32_bf16 v[104:107], v[44:47], v[212:215], v[104:107]
	v_add_u32_e32 v132, 0x800, v132
	v_add_u32_e32 v133, 0x1000, v133
	v_add_u32_e32 v134, 64, v134
	s_nop 4
	v_add_f32_e32 v108, v48, v96
	v_add_f32_e32 v109, v49, v97
	v_add_f32_e32 v110, v50, v98
	v_add_f32_e32 v111, v51, v99
	v_add_f32_e32 v112, v52, v100
	v_add_f32_e32 v113, v53, v101
	v_add_f32_e32 v114, v54, v102
	v_add_f32_e32 v115, v55, v103
	v_mul_f32_e32 v108, 0xbfb8aa3b, v108
	v_mul_f32_e32 v109, 0xbfb8aa3b, v109
	v_mul_f32_e32 v110, 0xbfb8aa3b, v110
	v_mul_f32_e32 v111, 0xbfb8aa3b, v111
	v_mul_f32_e32 v112, 0xbfb8aa3b, v112
	v_mul_f32_e32 v113, 0xbfb8aa3b, v113
	v_mul_f32_e32 v114, 0xbfb8aa3b, v114
	v_mul_f32_e32 v115, 0xbfb8aa3b, v115
	v_exp_f32_e32 v108, v108
	v_exp_f32_e32 v109, v109
	v_exp_f32_e32 v110, v110
	v_exp_f32_e32 v111, v111
	v_exp_f32_e32 v112, v112
	v_exp_f32_e32 v113, v113
	v_exp_f32_e32 v114, v114
	v_exp_f32_e32 v115, v115
	v_add_f32_e32 v108, 1.0, v108
	v_add_f32_e32 v109, 1.0, v109
	v_add_f32_e32 v110, 1.0, v110
	v_add_f32_e32 v111, 1.0, v111
	v_add_f32_e32 v112, 1.0, v112
	v_add_f32_e32 v113, 1.0, v113
	v_add_f32_e32 v114, 1.0, v114
	v_add_f32_e32 v115, 1.0, v115
	v_rcp_f32_e32 v108, v108
	v_rcp_f32_e32 v109, v109
	v_rcp_f32_e32 v110, v110
	v_rcp_f32_e32 v111, v111
	v_rcp_f32_e32 v112, v112
	v_rcp_f32_e32 v113, v113
	v_rcp_f32_e32 v114, v114
	v_rcp_f32_e32 v115, v115
	v_mul_f32_e32 v108, 0xbf60028b, v108
	v_mul_f32_e32 v109, 0xbf60028b, v109
	v_mul_f32_e32 v110, 0xbf60028b, v110
	v_mul_f32_e32 v111, 0xbf60028b, v111
	v_cvt_pk_bf16_f32 v116, v112, v113
	v_cvt_pk_bf16_f32 v117, v114, v115
	v_exp_f32_e32 v108, v108
	v_exp_f32_e32 v109, v109
	v_exp_f32_e32 v110, v110
	v_exp_f32_e32 v111, v111
	v_cvt_pk_bf16_f32 v118, v104, v105
	v_cvt_pk_bf16_f32 v119, v106, v107
	ds_write_b128 v128, v[108:111]
	ds_write_b64 v129, v[116:117] offset:1024
	ds_write_b64 v129, v[118:119] offset:1536
	s_waitcnt lgkmcnt(0)
	ds_read_b128 v[120:123], v130
	ds_read_b128 v[124:127], v130 offset:1024
	s_waitcnt lgkmcnt(0)
	global_store_dwordx4 v136, v[124:127], s[44:45]
	global_store_dwordx4 v135, v[120:123], s[54:55]
	v_add_u32_e32 v136, 32, v136
	v_add_u32_e32 v135, 64, v135
	s_branch .Llora_done
